# MLA fast loop unrolled x2 (even/odd tile): LDS ring parity static, base-address adds and parity SALU folded into DS immediate offsets
# baseline (speedup 1.0000x reference)
.Lf_962:
	s_or_b64 exec, exec, s[44:45]
	ds_read_b128 v[12:15], v212
	ds_read_b128 v[80:83], v212 offset:32
	ds_read_b128 v[84:87], v212 offset:64
	ds_read_b128 v[88:91], v212 offset:96
	ds_read_b128 v[92:95], v212 offset:128
	ds_read_b128 v[96:99], v212 offset:160
	s_waitcnt lgkmcnt(5)
	v_mfma_f32_32x32x16_bf16 v[128:143], v[12:15], v[188:191], 0
	v_mfma_f32_32x32x16_bf16 v[112:127], v[12:15], v[176:179], 0
	ds_read_b128 v[12:15], v212 offset:6656
	ds_read_b128 v[216:219], v212 offset:6688
	ds_read_b128 v[220:223], v212 offset:6720
	ds_read_b128 v[224:227], v212 offset:6752
	ds_read_b128 v[228:231], v212 offset:6784
	ds_read_b128 v[232:235], v212 offset:6816
	global_load_dwordx4 v[6:9], v[6:7], off
	s_waitcnt lgkmcnt(10)
	v_mfma_f32_32x32x16_bf16 v[128:143], v[80:83], v[184:187], v[128:143]
	v_mfma_f32_32x32x16_bf16 v[112:127], v[80:83], v[168:171], v[112:127]
	s_waitcnt lgkmcnt(9)
	v_mfma_f32_32x32x16_bf16 v[128:143], v[84:87], v[180:183], v[128:143]
	v_mfma_f32_32x32x16_bf16 v[112:127], v[84:87], v[164:167], v[112:127]
	s_waitcnt lgkmcnt(8)
	v_mfma_f32_32x32x16_bf16 v[128:143], v[88:91], v[172:175], v[128:143]
	v_mfma_f32_32x32x16_bf16 v[112:127], v[88:91], v[152:155], v[112:127]
	s_waitcnt lgkmcnt(7)
	v_mfma_f32_32x32x16_bf16 v[128:143], v[92:95], v[160:163], v[128:143]
	v_mfma_f32_32x32x16_bf16 v[112:127], v[92:95], v[148:151], v[112:127]
	s_waitcnt lgkmcnt(6)
	v_mfma_f32_32x32x16_bf16 v[128:143], v[96:99], v[156:159], v[128:143]
	v_mfma_f32_32x32x16_bf16 v[112:127], v[96:99], v[144:147], v[112:127]
	s_waitcnt lgkmcnt(5)
	v_mfma_f32_32x32x16_bf16 v[96:111], v[12:15], v[188:191], 0
	s_waitcnt lgkmcnt(4)
	v_mfma_f32_32x32x16_bf16 v[96:111], v[216:219], v[184:187], v[96:111]
	v_mfma_f32_32x32x16_bf16 v[80:95], v[12:15], v[176:179], 0
	s_waitcnt lgkmcnt(3)
	v_mfma_f32_32x32x16_bf16 v[96:111], v[220:223], v[180:183], v[96:111]
	v_mfma_f32_32x32x16_bf16 v[80:95], v[216:219], v[168:171], v[80:95]
	s_waitcnt lgkmcnt(2)
	v_mfma_f32_32x32x16_bf16 v[96:111], v[224:227], v[172:175], v[96:111]
	v_mfma_f32_32x32x16_bf16 v[80:95], v[220:223], v[164:167], v[80:95]
	s_waitcnt lgkmcnt(1)
	v_mfma_f32_32x32x16_bf16 v[96:111], v[228:231], v[160:163], v[96:111]
	v_mfma_f32_32x32x16_bf16 v[80:95], v[224:227], v[152:155], v[80:95]
	s_waitcnt lgkmcnt(0)
	v_mfma_f32_32x32x16_bf16 v[96:111], v[232:235], v[156:159], v[96:111]
	v_mfma_f32_32x32x16_bf16 v[80:95], v[228:231], v[148:151], v[80:95]
	v_mfma_f32_32x32x16_bf16 v[80:95], v[232:235], v[144:147], v[80:95]
	v_exp_f32_e32 v11, v128
	v_exp_f32_e32 v12, v129
	v_exp_f32_e32 v13, v130
	v_exp_f32_e32 v14, v131
	v_exp_f32_e32 v15, v132
	v_exp_f32_e32 v128, v133
	v_exp_f32_e32 v129, v134
	v_exp_f32_e32 v130, v135
	v_exp_f32_e32 v131, v136
	v_exp_f32_e32 v132, v137
	v_exp_f32_e32 v133, v138
	v_exp_f32_e32 v135, v140
	v_exp_f32_e32 v136, v141
	v_exp_f32_e32 v137, v142
	v_exp_f32_e32 v138, v143
	v_exp_f32_e32 v112, v112
	v_exp_f32_e32 v113, v113
	v_exp_f32_e32 v114, v114
	v_exp_f32_e32 v115, v115
	v_exp_f32_e32 v116, v116
	v_exp_f32_e32 v117, v117
	v_exp_f32_e32 v118, v118
	v_exp_f32_e32 v119, v119
	v_cvt_pk_bf16_f32 v140, v11, v12
	v_cvt_pk_bf16_f32 v141, v13, v14
	v_cvt_pk_bf16_f32 v142, v15, v128
	v_cvt_pk_bf16_f32 v143, v129, v130
	v_cvt_pk_bf16_f32 v216, v112, v113
	v_cvt_pk_bf16_f32 v217, v114, v115
	v_cvt_pk_bf16_f32 v218, v116, v117
	v_cvt_pk_bf16_f32 v219, v118, v119
	ds_read_b128 v[220:223], v210 offset:26624
	ds_read_b128 v[224:227], v210 offset:31232
	v_exp_f32_e32 v134, v139
	v_exp_f32_e32 v120, v120
	s_waitcnt lgkmcnt(1)
	v_mfma_f32_32x32x16_bf16 v[64:79], v[220:223], v[140:143], v[64:79]
	v_exp_f32_e32 v121, v121
	v_exp_f32_e32 v122, v122
	v_exp_f32_e32 v123, v123
	v_exp_f32_e32 v124, v124
	v_exp_f32_e32 v125, v125
	v_exp_f32_e32 v126, v126
	v_exp_f32_e32 v127, v127
	v_mfma_f32_32x32x16_bf16 v[32:47], v[220:223], v[216:219], v[32:47]
	v_cvt_pk_bf16_f32 v220, v131, v132
	v_cvt_pk_bf16_f32 v221, v133, v134
	v_cvt_pk_bf16_f32 v222, v135, v136
	v_cvt_pk_bf16_f32 v223, v137, v138
	v_cvt_pk_bf16_f32 v228, v120, v121
	v_cvt_pk_bf16_f32 v229, v122, v123
	v_cvt_pk_bf16_f32 v230, v124, v125
	v_cvt_pk_bf16_f32 v231, v126, v127
	ds_read_b128 v[232:235], v210 offset:26656
	s_waitcnt lgkmcnt(1)
	v_mfma_f32_32x32x16_bf16 v[16:31], v[224:227], v[216:219], v[16:31]
	ds_read_b128 v[216:219], v210 offset:31264
	v_exp_f32_e32 v237, v106
	v_exp_f32_e32 v106, v81
	v_exp_f32_e32 v139, v82
	v_mfma_f32_32x32x16_bf16 v[48:63], v[224:227], v[140:143], v[48:63]
	v_exp_f32_e32 v140, v83
	v_exp_f32_e32 v141, v84
	v_exp_f32_e32 v142, v85
	v_exp_f32_e32 v143, v86
	v_exp_f32_e32 v96, v96
	v_exp_f32_e32 v97, v97
	v_exp_f32_e32 v98, v98
	v_exp_f32_e32 v99, v99
	v_exp_f32_e32 v100, v100
	v_exp_f32_e32 v101, v101
	v_exp_f32_e32 v102, v102
	v_exp_f32_e32 v103, v103
	v_exp_f32_e32 v80, v80
	s_waitcnt lgkmcnt(1)
	v_mfma_f32_32x32x16_bf16 v[64:79], v[232:235], v[220:223], v[64:79]
	v_exp_f32_e32 v87, v87
	v_mfma_f32_32x32x16_bf16 v[32:47], v[232:235], v[228:231], v[32:47]
	s_waitcnt lgkmcnt(0)
	v_mfma_f32_32x32x16_bf16 v[48:63], v[216:219], v[220:223], v[48:63]
	v_cvt_pk_bf16_f32 v220, v96, v97
	v_cvt_pk_bf16_f32 v221, v98, v99
	v_cvt_pk_bf16_f32 v222, v100, v101
	v_cvt_pk_bf16_f32 v223, v102, v103
	v_cvt_pk_bf16_f32 v224, v80, v106
	v_cvt_pk_bf16_f32 v225, v139, v140
	v_cvt_pk_bf16_f32 v226, v141, v142
	v_cvt_pk_bf16_f32 v227, v143, v87
	ds_read_b128 v[232:235], v210 offset:26688
	v_mfma_f32_32x32x16_bf16 v[16:31], v[216:219], v[228:231], v[16:31]
	ds_read_b128 v[216:219], v210 offset:31296
	v_exp_f32_e32 v104, v104
	v_exp_f32_e32 v105, v105
	v_exp_f32_e32 v82, v107
	s_waitcnt lgkmcnt(1)
	v_mfma_f32_32x32x16_bf16 v[64:79], v[232:235], v[220:223], v[64:79]
	v_exp_f32_e32 v83, v108
	v_exp_f32_e32 v84, v109
	v_exp_f32_e32 v85, v110
	v_exp_f32_e32 v86, v111
	v_exp_f32_e32 v88, v88
	v_exp_f32_e32 v89, v89
	v_exp_f32_e32 v90, v90
	v_mfma_f32_32x32x16_bf16 v[32:47], v[232:235], v[224:227], v[32:47]
	v_exp_f32_e32 v91, v91
	v_exp_f32_e32 v92, v92
	v_exp_f32_e32 v93, v93
	v_exp_f32_e32 v94, v94
	v_exp_f32_e32 v95, v95
	v_cvt_pk_bf16_f32 v108, v104, v105
	v_cvt_pk_bf16_f32 v109, v237, v82
	s_waitcnt lgkmcnt(0)
	v_mfma_f32_32x32x16_bf16 v[48:63], v[216:219], v[220:223], v[48:63]
	v_cvt_pk_bf16_f32 v110, v83, v84
	v_cvt_pk_bf16_f32 v111, v85, v86
	v_mfma_f32_32x32x16_bf16 v[16:31], v[216:219], v[224:227], v[16:31]
	v_cvt_pk_bf16_f32 v216, v88, v89
	v_cvt_pk_bf16_f32 v217, v90, v91
	v_cvt_pk_bf16_f32 v218, v92, v93
	v_cvt_pk_bf16_f32 v219, v94, v95
	ds_read_b128 v[220:223], v210 offset:26720
	ds_read_b128 v[224:227], v210 offset:31328
	s_waitcnt vmcnt(1)
	ds_write_b128 v213, v[2:5] offset:13312
	s_waitcnt lgkmcnt(2)
	v_mfma_f32_32x32x16_bf16 v[64:79], v[220:223], v[108:111], v[64:79]
	v_mfma_f32_32x32x16_bf16 v[32:47], v[220:223], v[216:219], v[32:47]
	s_waitcnt lgkmcnt(1)
	v_mfma_f32_32x32x16_bf16 v[48:63], v[224:227], v[108:111], v[48:63]
	v_mfma_f32_32x32x16_bf16 v[16:31], v[224:227], v[216:219], v[16:31]
	s_and_saveexec_b64 s[44:45], s[0:1]
	s_cbranch_execz .Lf_966
	s_waitcnt vmcnt(0)
	ds_write_b128 v214, v[6:9] offset:13312
	v_mov_b64_e32 v[6:7], v[192:193]
	v_mov_b64_e32 v[8:9], v[194:195]
.Lf_966:
	s_or_b64 exec, exec, s[44:45]
	s_waitcnt vmcnt(0)
	ds_write_b128 v215, v[6:9] offset:35840
	v_pk_add_f32 v[244:245], v[88:89], v[90:91]
	v_pk_add_f32 v[246:247], v[92:93], v[94:95]
	v_pk_add_f32 v[244:245], v[244:245], v[112:113]
	v_pk_add_f32 v[246:247], v[246:247], v[114:115]
	v_pk_add_f32 v[244:245], v[244:245], v[116:117]
	v_pk_add_f32 v[246:247], v[246:247], v[118:119]
	v_pk_add_f32 v[244:245], v[244:245], v[120:121]
	v_pk_add_f32 v[246:247], v[246:247], v[122:123]
	v_pk_add_f32 v[244:245], v[244:245], v[124:125]
	v_pk_add_f32 v[246:247], v[246:247], v[126:127]
	v_pk_add_f32 v[244:245], v[244:245], v[140:141]
	v_pk_add_f32 v[246:247], v[246:247], v[142:143]
	v_pk_add_f32 v[244:245], v[244:245], v[246:247]
	v_add_f32_e32 v248, v244, v245
	v_add_f32_e32 v248, v80, v248
	v_add_f32_e32 v248, v87, v248
	v_add_f32_e32 v248, v106, v248
	v_add_f32_e32 v248, v139, v248
	v_add_f32_e32 v206, v206, v248
	v_pk_add_f32 v[244:245], v[12:13], v[14:15]
	v_pk_add_f32 v[246:247], v[82:83], v[84:85]
	v_pk_add_f32 v[244:245], v[244:245], v[96:97]
	v_pk_add_f32 v[246:247], v[246:247], v[98:99]
	v_pk_add_f32 v[244:245], v[244:245], v[100:101]
	v_pk_add_f32 v[246:247], v[246:247], v[102:103]
	v_pk_add_f32 v[244:245], v[244:245], v[104:105]
	v_pk_add_f32 v[246:247], v[246:247], v[128:129]
	v_pk_add_f32 v[244:245], v[244:245], v[130:131]
	v_pk_add_f32 v[246:247], v[246:247], v[132:133]
	v_pk_add_f32 v[244:245], v[244:245], v[134:135]
	v_pk_add_f32 v[246:247], v[246:247], v[136:137]
	v_pk_add_f32 v[244:245], v[244:245], v[246:247]
	v_add_f32_e32 v248, v244, v245
	v_add_f32_e32 v248, v11, v248
	v_add_f32_e32 v248, v86, v248
	v_add_f32_e32 v248, v138, v248
	v_add_f32_e32 v248, v237, v248
	v_add_f32_e32 v0, v0, v248
	v_lshl_add_u64 v[200:201], v[200:201], 0, s[10:11]
	s_cmp_eq_u32 s33, 63
	v_lshl_add_u64 v[202:203], v[202:203], 0, s[12:13]
	s_waitcnt lgkmcnt(0)
	s_barrier
	s_cbranch_scc1 .LBB0_970
	global_load_dwordx4 v[2:5], v[202:203], off
	s_add_i32 s33, s33, 1
	v_mov_b64_e32 v[6:7], v[200:201]
	s_and_saveexec_b64 s[44:45], s[0:1]
	s_cbranch_execz .Lf_962o
	global_load_dwordx4 v[192:195], v[200:201], off
	s_mul_i32 s6, s33, 0x1800
	s_lshl_b64 s[54:55], s[6:7], 1
	s_add_u32 s54, s42, s54
	s_addc_u32 s55, s43, s55
	v_lshl_add_u64 v[6:7], v[198:199], 1, s[54:55]
.Lf_962o:
	s_or_b64 exec, exec, s[44:45]
	ds_read_b128 v[12:15], v212 offset:13312
	ds_read_b128 v[80:83], v212 offset:13344
	ds_read_b128 v[84:87], v212 offset:13376
	ds_read_b128 v[88:91], v212 offset:13408
	ds_read_b128 v[92:95], v212 offset:13440
	ds_read_b128 v[96:99], v212 offset:13472
	s_waitcnt lgkmcnt(5)
	v_mfma_f32_32x32x16_bf16 v[128:143], v[12:15], v[188:191], 0
	v_mfma_f32_32x32x16_bf16 v[112:127], v[12:15], v[176:179], 0
	ds_read_b128 v[12:15], v212 offset:19968
	ds_read_b128 v[216:219], v212 offset:20000
	ds_read_b128 v[220:223], v212 offset:20032
	ds_read_b128 v[224:227], v212 offset:20064
	ds_read_b128 v[228:231], v212 offset:20096
	ds_read_b128 v[232:235], v212 offset:20128
	global_load_dwordx4 v[6:9], v[6:7], off
	s_waitcnt lgkmcnt(10)
	v_mfma_f32_32x32x16_bf16 v[128:143], v[80:83], v[184:187], v[128:143]
	v_mfma_f32_32x32x16_bf16 v[112:127], v[80:83], v[168:171], v[112:127]
	s_waitcnt lgkmcnt(9)
	v_mfma_f32_32x32x16_bf16 v[128:143], v[84:87], v[180:183], v[128:143]
	v_mfma_f32_32x32x16_bf16 v[112:127], v[84:87], v[164:167], v[112:127]
	s_waitcnt lgkmcnt(8)
	v_mfma_f32_32x32x16_bf16 v[128:143], v[88:91], v[172:175], v[128:143]
	v_mfma_f32_32x32x16_bf16 v[112:127], v[88:91], v[152:155], v[112:127]
	s_waitcnt lgkmcnt(7)
	v_mfma_f32_32x32x16_bf16 v[128:143], v[92:95], v[160:163], v[128:143]
	v_mfma_f32_32x32x16_bf16 v[112:127], v[92:95], v[148:151], v[112:127]
	s_waitcnt lgkmcnt(6)
	v_mfma_f32_32x32x16_bf16 v[128:143], v[96:99], v[156:159], v[128:143]
	v_mfma_f32_32x32x16_bf16 v[112:127], v[96:99], v[144:147], v[112:127]
	s_waitcnt lgkmcnt(5)
	v_mfma_f32_32x32x16_bf16 v[96:111], v[12:15], v[188:191], 0
	s_waitcnt lgkmcnt(4)
	v_mfma_f32_32x32x16_bf16 v[96:111], v[216:219], v[184:187], v[96:111]
	v_mfma_f32_32x32x16_bf16 v[80:95], v[12:15], v[176:179], 0
	s_waitcnt lgkmcnt(3)
	v_mfma_f32_32x32x16_bf16 v[96:111], v[220:223], v[180:183], v[96:111]
	v_mfma_f32_32x32x16_bf16 v[80:95], v[216:219], v[168:171], v[80:95]
	s_waitcnt lgkmcnt(2)
	v_mfma_f32_32x32x16_bf16 v[96:111], v[224:227], v[172:175], v[96:111]
	v_mfma_f32_32x32x16_bf16 v[80:95], v[220:223], v[164:167], v[80:95]
	s_waitcnt lgkmcnt(1)
	v_mfma_f32_32x32x16_bf16 v[96:111], v[228:231], v[160:163], v[96:111]
	v_mfma_f32_32x32x16_bf16 v[80:95], v[224:227], v[152:155], v[80:95]
	s_waitcnt lgkmcnt(0)
	v_mfma_f32_32x32x16_bf16 v[96:111], v[232:235], v[156:159], v[96:111]
	v_mfma_f32_32x32x16_bf16 v[80:95], v[228:231], v[148:151], v[80:95]
	v_mfma_f32_32x32x16_bf16 v[80:95], v[232:235], v[144:147], v[80:95]
	v_exp_f32_e32 v11, v128
	v_exp_f32_e32 v12, v129
	v_exp_f32_e32 v13, v130
	v_exp_f32_e32 v14, v131
	v_exp_f32_e32 v15, v132
	v_exp_f32_e32 v128, v133
	v_exp_f32_e32 v129, v134
	v_exp_f32_e32 v130, v135
	v_exp_f32_e32 v131, v136
	v_exp_f32_e32 v132, v137
	v_exp_f32_e32 v133, v138
	v_exp_f32_e32 v135, v140
	v_exp_f32_e32 v136, v141
	v_exp_f32_e32 v137, v142
	v_exp_f32_e32 v138, v143
	v_exp_f32_e32 v112, v112
	v_exp_f32_e32 v113, v113
	v_exp_f32_e32 v114, v114
	v_exp_f32_e32 v115, v115
	v_exp_f32_e32 v116, v116
	v_exp_f32_e32 v117, v117
	v_exp_f32_e32 v118, v118
	v_exp_f32_e32 v119, v119
	v_cvt_pk_bf16_f32 v140, v11, v12
	v_cvt_pk_bf16_f32 v141, v13, v14
	v_cvt_pk_bf16_f32 v142, v15, v128
	v_cvt_pk_bf16_f32 v143, v129, v130
	v_cvt_pk_bf16_f32 v216, v112, v113
	v_cvt_pk_bf16_f32 v217, v114, v115
	v_cvt_pk_bf16_f32 v218, v116, v117
	v_cvt_pk_bf16_f32 v219, v118, v119
	ds_read_b128 v[220:223], v210 offset:35840
	ds_read_b128 v[224:227], v210 offset:40448
	v_exp_f32_e32 v134, v139
	v_exp_f32_e32 v120, v120
	s_waitcnt lgkmcnt(1)
	v_mfma_f32_32x32x16_bf16 v[64:79], v[220:223], v[140:143], v[64:79]
	v_exp_f32_e32 v121, v121
	v_exp_f32_e32 v122, v122
	v_exp_f32_e32 v123, v123
	v_exp_f32_e32 v124, v124
	v_exp_f32_e32 v125, v125
	v_exp_f32_e32 v126, v126
	v_exp_f32_e32 v127, v127
	v_mfma_f32_32x32x16_bf16 v[32:47], v[220:223], v[216:219], v[32:47]
	v_cvt_pk_bf16_f32 v220, v131, v132
	v_cvt_pk_bf16_f32 v221, v133, v134
	v_cvt_pk_bf16_f32 v222, v135, v136
	v_cvt_pk_bf16_f32 v223, v137, v138
	v_cvt_pk_bf16_f32 v228, v120, v121
	v_cvt_pk_bf16_f32 v229, v122, v123
	v_cvt_pk_bf16_f32 v230, v124, v125
	v_cvt_pk_bf16_f32 v231, v126, v127
	ds_read_b128 v[232:235], v210 offset:35872
	s_waitcnt lgkmcnt(1)
	v_mfma_f32_32x32x16_bf16 v[16:31], v[224:227], v[216:219], v[16:31]
	ds_read_b128 v[216:219], v210 offset:40480
	v_exp_f32_e32 v237, v106
	v_exp_f32_e32 v106, v81
	v_exp_f32_e32 v139, v82
	v_mfma_f32_32x32x16_bf16 v[48:63], v[224:227], v[140:143], v[48:63]
	v_exp_f32_e32 v140, v83
	v_exp_f32_e32 v141, v84
	v_exp_f32_e32 v142, v85
	v_exp_f32_e32 v143, v86
	v_exp_f32_e32 v96, v96
	v_exp_f32_e32 v97, v97
	v_exp_f32_e32 v98, v98
	v_exp_f32_e32 v99, v99
	v_exp_f32_e32 v100, v100
	v_exp_f32_e32 v101, v101
	v_exp_f32_e32 v102, v102
	v_exp_f32_e32 v103, v103
	v_exp_f32_e32 v80, v80
	s_waitcnt lgkmcnt(1)
	v_mfma_f32_32x32x16_bf16 v[64:79], v[232:235], v[220:223], v[64:79]
	v_exp_f32_e32 v87, v87
	v_mfma_f32_32x32x16_bf16 v[32:47], v[232:235], v[228:231], v[32:47]
	s_waitcnt lgkmcnt(0)
	v_mfma_f32_32x32x16_bf16 v[48:63], v[216:219], v[220:223], v[48:63]
	v_cvt_pk_bf16_f32 v220, v96, v97
	v_cvt_pk_bf16_f32 v221, v98, v99
	v_cvt_pk_bf16_f32 v222, v100, v101
	v_cvt_pk_bf16_f32 v223, v102, v103
	v_cvt_pk_bf16_f32 v224, v80, v106
	v_cvt_pk_bf16_f32 v225, v139, v140
	v_cvt_pk_bf16_f32 v226, v141, v142
	v_cvt_pk_bf16_f32 v227, v143, v87
	ds_read_b128 v[232:235], v210 offset:35904
	v_mfma_f32_32x32x16_bf16 v[16:31], v[216:219], v[228:231], v[16:31]
	ds_read_b128 v[216:219], v210 offset:40512
	v_exp_f32_e32 v104, v104
	v_exp_f32_e32 v105, v105
	v_exp_f32_e32 v82, v107
	s_waitcnt lgkmcnt(1)
	v_mfma_f32_32x32x16_bf16 v[64:79], v[232:235], v[220:223], v[64:79]
	v_exp_f32_e32 v83, v108
	v_exp_f32_e32 v84, v109
	v_exp_f32_e32 v85, v110
	v_exp_f32_e32 v86, v111
	v_exp_f32_e32 v88, v88
	v_exp_f32_e32 v89, v89
	v_exp_f32_e32 v90, v90
	v_mfma_f32_32x32x16_bf16 v[32:47], v[232:235], v[224:227], v[32:47]
	v_exp_f32_e32 v91, v91
	v_exp_f32_e32 v92, v92
	v_exp_f32_e32 v93, v93
	v_exp_f32_e32 v94, v94
	v_exp_f32_e32 v95, v95
	v_cvt_pk_bf16_f32 v108, v104, v105
	v_cvt_pk_bf16_f32 v109, v237, v82
	s_waitcnt lgkmcnt(0)
	v_mfma_f32_32x32x16_bf16 v[48:63], v[216:219], v[220:223], v[48:63]
	v_cvt_pk_bf16_f32 v110, v83, v84
	v_cvt_pk_bf16_f32 v111, v85, v86
	v_mfma_f32_32x32x16_bf16 v[16:31], v[216:219], v[224:227], v[16:31]
	v_cvt_pk_bf16_f32 v216, v88, v89
	v_cvt_pk_bf16_f32 v217, v90, v91
	v_cvt_pk_bf16_f32 v218, v92, v93
	v_cvt_pk_bf16_f32 v219, v94, v95
	ds_read_b128 v[220:223], v210 offset:35936
	ds_read_b128 v[224:227], v210 offset:40544
	s_waitcnt vmcnt(1)
	ds_write_b128 v213, v[2:5]
	s_waitcnt lgkmcnt(2)
	v_mfma_f32_32x32x16_bf16 v[64:79], v[220:223], v[108:111], v[64:79]
	v_mfma_f32_32x32x16_bf16 v[32:47], v[220:223], v[216:219], v[32:47]
	s_waitcnt lgkmcnt(1)
	v_mfma_f32_32x32x16_bf16 v[48:63], v[224:227], v[108:111], v[48:63]
	v_mfma_f32_32x32x16_bf16 v[16:31], v[224:227], v[216:219], v[16:31]
	s_and_saveexec_b64 s[44:45], s[0:1]
	s_cbranch_execz .Lf_966o
	s_waitcnt vmcnt(0)
	ds_write_b128 v214, v[6:9]
	v_mov_b64_e32 v[6:7], v[192:193]
	v_mov_b64_e32 v[8:9], v[194:195]
.Lf_966o:
	s_or_b64 exec, exec, s[44:45]
	s_waitcnt vmcnt(0)
	ds_write_b128 v215, v[6:9] offset:26624
	v_pk_add_f32 v[244:245], v[88:89], v[90:91]
	v_pk_add_f32 v[246:247], v[92:93], v[94:95]
	v_pk_add_f32 v[244:245], v[244:245], v[112:113]
	v_pk_add_f32 v[246:247], v[246:247], v[114:115]
	v_pk_add_f32 v[244:245], v[244:245], v[116:117]
	v_pk_add_f32 v[246:247], v[246:247], v[118:119]
	v_pk_add_f32 v[244:245], v[244:245], v[120:121]
	v_pk_add_f32 v[246:247], v[246:247], v[122:123]
	v_pk_add_f32 v[244:245], v[244:245], v[124:125]
	v_pk_add_f32 v[246:247], v[246:247], v[126:127]
	v_pk_add_f32 v[244:245], v[244:245], v[140:141]
	v_pk_add_f32 v[246:247], v[246:247], v[142:143]
	v_pk_add_f32 v[244:245], v[244:245], v[246:247]
	v_add_f32_e32 v248, v244, v245
	v_add_f32_e32 v248, v80, v248
	v_add_f32_e32 v248, v87, v248
	v_add_f32_e32 v248, v106, v248
	v_add_f32_e32 v248, v139, v248
	v_add_f32_e32 v206, v206, v248
	v_pk_add_f32 v[244:245], v[12:13], v[14:15]
	v_pk_add_f32 v[246:247], v[82:83], v[84:85]
	v_pk_add_f32 v[244:245], v[244:245], v[96:97]
	v_pk_add_f32 v[246:247], v[246:247], v[98:99]
	v_pk_add_f32 v[244:245], v[244:245], v[100:101]
	v_pk_add_f32 v[246:247], v[246:247], v[102:103]
	v_pk_add_f32 v[244:245], v[244:245], v[104:105]
	v_pk_add_f32 v[246:247], v[246:247], v[128:129]
	v_pk_add_f32 v[244:245], v[244:245], v[130:131]
	v_pk_add_f32 v[246:247], v[246:247], v[132:133]
	v_pk_add_f32 v[244:245], v[244:245], v[134:135]
	v_pk_add_f32 v[246:247], v[246:247], v[136:137]
	v_pk_add_f32 v[244:245], v[244:245], v[246:247]
	v_add_f32_e32 v248, v244, v245
	v_add_f32_e32 v248, v11, v248
	v_add_f32_e32 v248, v86, v248
	v_add_f32_e32 v248, v138, v248
	v_add_f32_e32 v248, v237, v248
	v_add_f32_e32 v0, v0, v248
	v_lshl_add_u64 v[200:201], v[200:201], 0, s[10:11]
	v_lshl_add_u64 v[202:203], v[202:203], 0, s[12:13]
	s_waitcnt lgkmcnt(0)
	s_barrier
	s_mov_b32 s24, s33
	s_branch .Lf_960
